# XCD-local barriers: L1 invalidate issued right after arrival (overlaps the release wait)
# baseline (speedup 1.0000x reference)
.LBB0_430:
	s_or_b64 exec, exec, s[42:43]
	s_waitcnt vmcnt(0)
	buffer_inv sc1
	v_readfirstlane_b32 s6, v2
	s_waitcnt lgkmcnt(0)
	v_cvt_f32_u32_e32 v2, v0
	v_sub_u32_e32 v3, 0, v0
	v_add_u32_e32 v1, s6, v1
	v_readlane_b32 s20, v254, 63
	v_rcp_iflag_f32_e32 v2, v2
	v_readlane_b32 s21, v255, 0
	s_mov_b64 s[42:43], -1
	v_mul_f32_e32 v2, 0x4f7ffffe, v2
	v_cvt_u32_f32_e32 v2, v2
	v_mul_lo_u32 v3, v3, v2
	v_mul_hi_u32 v3, v2, v3
	v_add_u32_e32 v2, v2, v3
	v_mul_hi_u32 v2, v1, v2
	v_mul_lo_u32 v3, v2, v0
	v_sub_u32_e32 v3, v1, v3
	v_cmp_ge_u32_e32 vcc, v3, v0
	v_add_u32_e32 v4, 1, v2
	v_add_u32_e32 v1, 1, v1
	v_cndmask_b32_e32 v2, v2, v4, vcc
	v_sub_u32_e32 v4, v3, v0
	v_cndmask_b32_e32 v3, v3, v4, vcc
	v_cmp_ge_u32_e32 vcc, v3, v0
	v_add_u32_e32 v3, 1, v2
	s_nop 0
	v_cndmask_b32_e32 v2, v2, v3, vcc
	v_mul_lo_u32 v3, v0, v2
	v_add_u32_e32 v0, v3, v0
	v_cmp_ne_u32_e32 vcc, v1, v0
	v_mov_b64_e32 v[0:1], s[20:21]
	s_and_saveexec_b64 s[40:41], vcc
	s_cbranch_execz .LBB0_442
	v_readlane_b32 s20, v254, 63
	v_readlane_b32 s21, v255, 0
	s_mov_b64 s[44:45], 0
	s_nop 3
	global_load_dword v0, v49, s[20:21] sc1
	s_waitcnt vmcnt(0)
	v_cmp_eq_u32_e32 vcc, v0, v2
	s_and_saveexec_b64 s[42:43], vcc
	s_cbranch_execz .LBB0_441
	s_mov_b32 s6, 1
	s_branch .LBB0_434

.LBB0_444:
	s_or_b64 exec, exec, s[40:41]
	s_waitcnt vmcnt(0)
	s_waitcnt vmcnt(0)

.LBB0_756:
	s_or_b64 exec, exec, s[44:45]
	s_waitcnt vmcnt(0)
	buffer_inv sc1
	v_readfirstlane_b32 s6, v2
	s_waitcnt lgkmcnt(0)
	v_cvt_f32_u32_e32 v2, v0
	v_sub_u32_e32 v3, 0, v0
	v_add_u32_e32 v1, s6, v1
	v_readlane_b32 s8, v254, 63
	v_rcp_iflag_f32_e32 v2, v2
	v_readlane_b32 s9, v255, 0
	s_mov_b64 s[44:45], -1
	v_mul_f32_e32 v2, 0x4f7ffffe, v2
	v_cvt_u32_f32_e32 v2, v2
	v_mul_lo_u32 v3, v3, v2
	v_mul_hi_u32 v3, v2, v3
	v_add_u32_e32 v2, v2, v3
	v_mul_hi_u32 v2, v1, v2
	v_mul_lo_u32 v3, v2, v0
	v_sub_u32_e32 v3, v1, v3
	v_cmp_ge_u32_e32 vcc, v3, v0
	v_add_u32_e32 v4, 1, v2
	v_add_u32_e32 v1, 1, v1
	v_cndmask_b32_e32 v2, v2, v4, vcc
	v_sub_u32_e32 v4, v3, v0
	v_cndmask_b32_e32 v3, v3, v4, vcc
	v_cmp_ge_u32_e32 vcc, v3, v0
	v_add_u32_e32 v3, 1, v2
	s_nop 0
	v_cndmask_b32_e32 v2, v2, v3, vcc
	v_mul_lo_u32 v3, v0, v2
	v_add_u32_e32 v0, v3, v0
	v_cmp_ne_u32_e32 vcc, v1, v0
	v_mov_b64_e32 v[0:1], s[8:9]
	s_and_saveexec_b64 s[42:43], vcc
	s_cbranch_execz .LBB0_768
	v_readlane_b32 s8, v254, 63
	v_readlane_b32 s9, v255, 0
	s_mov_b64 s[46:47], 0
	s_nop 3
	global_load_dword v0, v49, s[8:9] sc1
	s_waitcnt vmcnt(0)
	v_cmp_eq_u32_e32 vcc, v0, v2
	s_and_saveexec_b64 s[44:45], vcc
	s_cbranch_execz .LBB0_767
	s_mov_b32 s6, 1
	s_branch .LBB0_760

.LBB0_770:
	s_or_b64 exec, exec, s[42:43]
	s_waitcnt vmcnt(0)
	s_waitcnt vmcnt(0)

.LBB0_1012:
	s_or_b64 exec, exec, s[44:45]
	s_waitcnt vmcnt(0)
	buffer_inv sc1
	v_readfirstlane_b32 s6, v2
	s_waitcnt lgkmcnt(0)
	v_cvt_f32_u32_e32 v2, v0
	v_sub_u32_e32 v3, 0, v0
	v_add_u32_e32 v1, s6, v1
	v_readlane_b32 s6, v254, 63
	v_rcp_iflag_f32_e32 v2, v2
	v_readlane_b32 s7, v255, 0
	s_mov_b64 s[44:45], -1
	v_mul_f32_e32 v2, 0x4f7ffffe, v2
	v_cvt_u32_f32_e32 v2, v2
	v_mul_lo_u32 v3, v3, v2
	v_mul_hi_u32 v3, v2, v3
	v_add_u32_e32 v2, v2, v3
	v_mul_hi_u32 v2, v1, v2
	v_mul_lo_u32 v3, v2, v0
	v_sub_u32_e32 v3, v1, v3
	v_cmp_ge_u32_e32 vcc, v3, v0
	v_add_u32_e32 v4, 1, v2
	v_add_u32_e32 v1, 1, v1
	v_cndmask_b32_e32 v2, v2, v4, vcc
	v_sub_u32_e32 v4, v3, v0
	v_cndmask_b32_e32 v3, v3, v4, vcc
	v_cmp_ge_u32_e32 vcc, v3, v0
	v_add_u32_e32 v3, 1, v2
	s_nop 0
	v_cndmask_b32_e32 v2, v2, v3, vcc
	v_mul_lo_u32 v3, v0, v2
	v_add_u32_e32 v0, v3, v0
	v_cmp_ne_u32_e32 vcc, v1, v0
	v_mov_b64_e32 v[0:1], s[6:7]
	s_and_saveexec_b64 s[42:43], vcc
	s_cbranch_execz .LBB0_1024
	v_readlane_b32 s6, v254, 63
	v_readlane_b32 s7, v255, 0
	s_mov_b64 s[46:47], 0
	s_nop 3
	global_load_dword v0, v49, s[6:7] sc1
	s_waitcnt vmcnt(0)
	v_cmp_eq_u32_e32 vcc, v0, v2
	s_and_saveexec_b64 s[44:45], vcc
	s_cbranch_execz .LBB0_1023
	s_mov_b32 s6, 1
	s_branch .LBB0_1016

.LBB0_1179:
	s_or_b64 exec, exec, s[42:43]
	s_waitcnt vmcnt(0)
	buffer_inv sc1
	v_readfirstlane_b32 s6, v2
	s_waitcnt lgkmcnt(0)
	v_cvt_f32_u32_e32 v2, v0
	v_sub_u32_e32 v3, 0, v0
	v_add_u32_e32 v1, s6, v1
	v_readlane_b32 s6, v254, 63
	v_rcp_iflag_f32_e32 v2, v2
	v_readlane_b32 s7, v255, 0
	s_mov_b64 s[42:43], -1
	v_mul_f32_e32 v2, 0x4f7ffffe, v2
	v_cvt_u32_f32_e32 v2, v2
	v_mul_lo_u32 v3, v3, v2
	v_mul_hi_u32 v3, v2, v3
	v_add_u32_e32 v2, v2, v3
	v_mul_hi_u32 v2, v1, v2
	v_mul_lo_u32 v3, v2, v0
	v_sub_u32_e32 v3, v1, v3
	v_cmp_ge_u32_e32 vcc, v3, v0
	v_add_u32_e32 v4, 1, v2
	v_add_u32_e32 v1, 1, v1
	v_cndmask_b32_e32 v2, v2, v4, vcc
	v_sub_u32_e32 v4, v3, v0
	v_cndmask_b32_e32 v3, v3, v4, vcc
	v_cmp_ge_u32_e32 vcc, v3, v0
	v_add_u32_e32 v3, 1, v2
	s_nop 0
	v_cndmask_b32_e32 v2, v2, v3, vcc
	v_mul_lo_u32 v3, v0, v2
	v_add_u32_e32 v0, v3, v0
	v_cmp_ne_u32_e32 vcc, v1, v0
	v_mov_b64_e32 v[0:1], s[6:7]
	s_and_saveexec_b64 s[40:41], vcc
	s_cbranch_execz .LBB0_1191
	v_readlane_b32 s6, v254, 63
	v_readlane_b32 s7, v255, 0
	s_mov_b64 s[44:45], 0
	s_nop 3
	global_load_dword v0, v49, s[6:7] sc1
	s_waitcnt vmcnt(0)
	v_cmp_eq_u32_e32 vcc, v0, v2
	s_and_saveexec_b64 s[42:43], vcc
	s_cbranch_execz .LBB0_1190
	s_mov_b32 s6, 1
	s_branch .LBB0_1183

.LBB0_1263:
	s_or_b64 exec, exec, s[40:41]
	s_waitcnt vmcnt(0)
	buffer_inv sc1
	v_readfirstlane_b32 s6, v2
	s_waitcnt lgkmcnt(0)
	v_cvt_f32_u32_e32 v2, v0
	v_sub_u32_e32 v3, 0, v0
	v_add_u32_e32 v1, s6, v1
	v_readlane_b32 s6, v254, 63
	v_rcp_iflag_f32_e32 v2, v2
	v_readlane_b32 s7, v255, 0
	s_mov_b64 s[40:41], -1
	v_mul_f32_e32 v2, 0x4f7ffffe, v2
	v_cvt_u32_f32_e32 v2, v2
	v_mul_lo_u32 v3, v3, v2
	v_mul_hi_u32 v3, v2, v3
	v_add_u32_e32 v2, v2, v3
	v_mul_hi_u32 v2, v1, v2
	v_mul_lo_u32 v3, v2, v0
	v_sub_u32_e32 v3, v1, v3
	v_cmp_ge_u32_e32 vcc, v3, v0
	v_add_u32_e32 v4, 1, v2
	v_add_u32_e32 v1, 1, v1
	v_cndmask_b32_e32 v2, v2, v4, vcc
	v_sub_u32_e32 v4, v3, v0
	v_cndmask_b32_e32 v3, v3, v4, vcc
	v_cmp_ge_u32_e32 vcc, v3, v0
	v_add_u32_e32 v3, 1, v2
	s_nop 0
	v_cndmask_b32_e32 v2, v2, v3, vcc
	v_mul_lo_u32 v3, v0, v2
	v_add_u32_e32 v0, v3, v0
	v_cmp_ne_u32_e32 vcc, v1, v0
	v_mov_b64_e32 v[0:1], s[6:7]
	s_and_saveexec_b64 s[38:39], vcc
	s_cbranch_execz .LBB0_1275
	v_readlane_b32 s6, v254, 63
	v_readlane_b32 s7, v255, 0
	s_mov_b64 s[42:43], 0
	s_nop 3
	global_load_dword v0, v49, s[6:7] sc1
	s_waitcnt vmcnt(0)
	v_cmp_eq_u32_e32 vcc, v0, v2
	s_and_saveexec_b64 s[40:41], vcc
	s_cbranch_execz .LBB0_1274
	s_mov_b32 s6, 1
	s_branch .LBB0_1267

.LBB0_1277:
	s_or_b64 exec, exec, s[38:39]
	s_waitcnt vmcnt(0)
	s_waitcnt vmcnt(0)

.LBB0_1383:
	s_or_b64 exec, exec, s[40:41]
	s_waitcnt vmcnt(0)
	buffer_inv sc1
	v_readfirstlane_b32 s6, v2
	s_waitcnt lgkmcnt(0)
	v_cvt_f32_u32_e32 v2, v0
	v_sub_u32_e32 v3, 0, v0
	v_add_u32_e32 v1, s6, v1
	v_readlane_b32 s8, v254, 63
	v_rcp_iflag_f32_e32 v2, v2
	v_readlane_b32 s9, v255, 0
	s_mov_b64 s[40:41], -1
	v_mul_f32_e32 v2, 0x4f7ffffe, v2
	v_cvt_u32_f32_e32 v2, v2
	v_mul_lo_u32 v3, v3, v2
	v_mul_hi_u32 v3, v2, v3
	v_add_u32_e32 v2, v2, v3
	v_mul_hi_u32 v2, v1, v2
	v_mul_lo_u32 v3, v2, v0
	v_sub_u32_e32 v3, v1, v3
	v_cmp_ge_u32_e32 vcc, v3, v0
	v_add_u32_e32 v4, 1, v2
	v_add_u32_e32 v1, 1, v1
	v_cndmask_b32_e32 v2, v2, v4, vcc
	v_sub_u32_e32 v4, v3, v0
	v_cndmask_b32_e32 v3, v3, v4, vcc
	v_cmp_ge_u32_e32 vcc, v3, v0
	v_add_u32_e32 v3, 1, v2
	s_nop 0
	v_cndmask_b32_e32 v2, v2, v3, vcc
	v_mul_lo_u32 v3, v0, v2
	v_add_u32_e32 v0, v3, v0
	v_cmp_ne_u32_e32 vcc, v1, v0
	v_mov_b64_e32 v[0:1], s[8:9]
	s_and_saveexec_b64 s[38:39], vcc
	s_cbranch_execz .LBB0_1395
	v_readlane_b32 s8, v254, 63
	v_readlane_b32 s9, v255, 0
	s_mov_b64 s[42:43], 0
	s_nop 3
	global_load_dword v0, v49, s[8:9] sc1
	s_waitcnt vmcnt(0)
	v_cmp_eq_u32_e32 vcc, v0, v2
	s_and_saveexec_b64 s[40:41], vcc
	s_cbranch_execz .LBB0_1394
	s_mov_b32 s6, 1
	s_branch .LBB0_1387
